# row-split also for AB-out / C-out sample-row GEMMs (K=1024); final copy loop issues both loads before one wait
# speedup vs baseline: 1.0145x; 1.0016x over previous
; #define LAS __attribute__((address_space(3)))
; __device__ __forceinline__ void small_resid(LAS unsigned char* lds, const bf16_t* A, int K, const bf16_t* Bt, const float* xs_in, float* X, const float* modp, float coef, ...
;     for (int un = c; un < 64; un += G) {
;         f32x4 o[1]; small_core<1>(lds, A, K, Bt + (size_t)(16 * un) * K, Bt, K, o);
;         const int row = threadIdx.x >> 2, col = 16 * un + (threadIdx.x & 3) * 4, b = 16 + (row >> 4);
;         f32x4 bs;
;         if (xs_in) bs = *(const f32x4*)(xs_in + (size_t)row * DM + col);
;         else { const u32x2 r_ = *(const u32x2*)(An + (size_t)(NP + row) * DM + col); const f32x4 rg = *(const f32x4*)(rgs + (size_t)b * 1024 + col);
; __global__ void __launch_bounds__(512, 2) fwd_kernel(Params P) {
;     ...
;         small_resid(lds, OAB + (size_t)NP * DM, 1024, WABO, nullptr, X, MOD + (size_t)5 * 1024, 1.0f, SSQ + 2 * 33024, GS + 2 * 24 * 1024, RGS + 1 * 24 * 1024, H, true, G, c);
.LBB0_876:
	s_add_u32 s18, s92, 0x5000
	s_addc_u32 s19, s93, 0
	s_add_u32 s20, s92, 0x1e2c0000
	v_readlane_b32 s0, v254, 60
	s_addc_u32 s21, s93, 0
	v_readlane_b32 s1, v254, 61
	s_add_u32 s22, s92, 0x1e83fc00
	s_addc_u32 s23, s93, 0
	v_cndmask_b32_e64 v0, 0, 1, s[0:1]
	v_cmp_ne_u32_e64 s[6:7], 1, v0
	s_andn2_b64 vcc, exec, s[0:1]
	v_readlane_b32 s50, v255, 26
	s_and_b32 s99, s2, 3
	s_mov_b32 s101, 0
	v_lshlrev_b32_e32 v0, 9, v178
	v_readlane_b32 s8, v254, 3
	v_and_b32_e32 v32, 0x7f800, v0
	v_mov_b32_e32 v33, 0
	v_readlane_b32 s10, v254, 5
	v_readlane_b32 s11, v254, 6
	v_readlane_b32 s14, v254, 9
	v_readlane_b32 s15, v254, 10
	v_or_b32_e32 v2, 16, v179
	v_lshl_add_u32 v2, s99, 1, v2
	v_lshl_add_u64 v[0:1], s[42:43], 0, v[32:33]
	s_mov_b64 s[0:1], 0x4000000
	s_mov_b64 s[10:11], s[14:15]
	v_lshl_add_u64 v[34:35], v[0:1], 0, s[0:1]
	s_mul_i32 s100, s99, 0x10000
	v_lshl_add_u64 v[34:35], v[34:35], 0, s[100:101]
	v_lshlrev_b32_e32 v32, 12, v2
	s_mov_b32 s0, 0x9000
	v_mov_b64_e32 v[0:1], s[18:19]
	s_add_u32 s4, s10, 0x16928000
	v_lshl_add_u64 v[36:37], s[22:23], 0, v[32:33]
	v_mad_u64_u32 v[38:39], s[0:1], v2, s0, v[0:1]
	v_lshl_add_u64 v[40:41], s[20:21], 0, v[32:33]
	v_and_b32_e32 v0, 3, v178
	v_and_b32_e32 v32, 0x3fc, v178
	v_readlane_b32 s9, v254, 4
	v_readlane_b32 s12, v254, 7
	v_readlane_b32 s13, v254, 8
	s_addc_u32 s5, s11, 0
	v_cmp_eq_u32_e64 s[0:1], 0, v0
	v_lshl_add_u64 v[0:1], s[92:93], 0, v[32:33]
	s_mov_b64 s[10:11], 0x1e7a6800
	s_waitcnt vmcnt(1)
	v_and_b32_e32 v64, 12, v239
	s_mov_b32 s9, 0
	v_lshl_add_u64 v[42:43], v[0:1], 0, s[10:11]
	s_mul_i32 s100, s99, 0x80
	v_lshl_add_u64 v[42:43], v[42:43], 0, s[100:101]
	s_mov_b64 s[10:11], 0x8000
	s_mov_b64 s[12:13], 0x10000
	s_mov_b64 s[14:15], 0x18000
	s_mov_b64 s[16:17], 0x20000
	s_mov_b64 s[34:35], 0x28000
	s_mov_b64 s[36:37], 0x30000
	s_mov_b64 s[38:39], 0x38000
	s_mul_hi_u32 s3, s2, 0x40000000
	s_branch .LBB0_879

; #define LAS __attribute__((address_space(3)))
; template <int NB>
; __device__ __forceinline__ void small_core(LAS unsigned char* lds, const bf16_t* A, int lda, const bf16_t* B0, const bf16_t* B1, int K, f32x4 (&out)[NB]) {
;     int tid_ = threadIdx.x; asm volatile("" : "+v"(tid_));
;     const int tid = tid_, lane = tid & 63, w = __builtin_amdgcn_readfirstlane(tid >> 6), fr = lane & 15, fq = lane >> 4;
;     f32x4 acc[NB][8];
; #pragma unroll
;     for (int nb = 0; nb < NB; ++nb)
; #pragma unroll
;         for (int mb = 0; mb < 8; ++mb) acc[nb][mb] = (f32x4){0.f, 0.f, 0.f, 0.f};
;     const bf16_t* ap = A + (size_t)fr * lda + 8 * fq;
;     const bf16_t* bp0 = B0 + (size_t)fr * K + 8 * fq;
;     const bf16_t* bp1 = B1 + (size_t)fr * K + 8 * fq;
;     const int nsteps = K >> 5;
;     int st = w;
;     for (; st + 8 < nsteps; st += 16) {
;         const int k = st * 32, k2 = k + 256;
;         bf16x8 b[NB], b2[NB]; b[0] = *(const bf16x8*)(bp0 + k); b2[0] = *(const bf16x8*)(bp0 + k2);
;         if (NB == 2) { b[NB - 1] = *(const bf16x8*)(bp1 + k); b2[NB - 1] = *(const bf16x8*)(bp1 + k2); }
;         bf16x8 a[8], a2[8];
; #pragma unroll
;         for (int mb = 0; mb < 8; ++mb) { a[mb] = *(const bf16x8*)(ap + (size_t)(16 * mb) * lda + k); a2[mb] = *(const bf16x8*)(ap + (size_t)(16 * mb) * lda + k2); }
; #pragma unroll
;         for (int mb = 0; mb < 8; ++mb)
; #pragma unroll
;             for (int nb = 0; nb < NB; ++nb) { acc[nb][mb] = __builtin_amdgcn_mfma_f32_16x16x32_bf16(b[nb], a[mb], acc[nb][mb], 0, 0, 0);
;                 acc[nb][mb] = __builtin_amdgcn_mfma_f32_16x16x32_bf16(b2[nb], a2[mb], acc[nb][mb], 0, 0, 0); }
;     }
.LBB0_879:
	s_lshl_b32 s40, s3, 4
	s_ashr_i32 s41, s40, 31
	v_mov_b32_e32 v65, v178
	s_lshl_b64 s[46:47], s[40:41], 11
	s_add_u32 s46, s86, s46
	v_and_b32_e32 v66, 15, v65
	v_bfe_u32 v2, v65, 4, 2
	v_lshlrev_b32_e32 v32, 11, v66
	s_addc_u32 s47, s87, s47
	v_readfirstlane_b32 s8, v65
	s_waitcnt lgkmcnt(0)
	v_lshl_add_u64 v[0:1], s[4:5], 0, v[32:33]
	v_lshlrev_b32_e32 v44, 4, v2
	v_mov_b32_e32 v45, v33
	s_ashr_i32 s25, s8, 6
	v_lshl_add_u64 v[46:47], v[0:1], 0, v[44:45]
	s_mul_i32 s100, s99, 0x10000
	v_lshl_add_u64 v[46:47], v[46:47], 0, s[100:101]
	v_lshl_add_u64 v[0:1], s[46:47], 0, v[32:33]
	v_lshl_add_u64 v[48:49], v[0:1], 0, v[44:45]
	s_cmp_gt_i32 s25, 23
	v_mov_b32_e32 v3, 0
	v_mov_b32_e32 v2, 0
	v_mov_b32_e32 v1, 0
	v_mov_b32_e32 v0, 0
	v_mov_b32_e32 v7, 0
	v_mov_b32_e32 v6, 0
	v_mov_b32_e32 v5, 0
	v_mov_b32_e32 v4, 0
	v_mov_b32_e32 v11, 0
	v_mov_b32_e32 v10, 0
	v_mov_b32_e32 v9, 0
	v_mov_b32_e32 v8, 0
	v_mov_b32_e32 v15, 0
	v_mov_b32_e32 v14, 0
	v_mov_b32_e32 v13, 0
	v_mov_b32_e32 v12, 0
	v_mov_b32_e32 v19, 0
	v_mov_b32_e32 v18, 0
	v_mov_b32_e32 v17, 0
	v_mov_b32_e32 v16, 0
	v_mov_b32_e32 v23, 0
	v_mov_b32_e32 v22, 0
	v_mov_b32_e32 v21, 0
	v_mov_b32_e32 v20, 0
	v_mov_b32_e32 v27, 0
	v_mov_b32_e32 v26, 0
	v_mov_b32_e32 v25, 0
	v_mov_b32_e32 v24, 0
	v_mov_b32_e32 v31, 0
	v_mov_b32_e32 v30, 0
	v_mov_b32_e32 v29, 0
	v_mov_b32_e32 v28, 0
	s_mov_b32 s8, s25
	s_cbranch_scc1 .LBB0_882
	v_mov_b32_e32 v28, 0
	v_lshl_add_u64 v[50:51], v[46:47], 0, s[10:11]
	v_lshl_add_u64 v[52:53], v[46:47], 0, s[12:13]
	v_lshl_add_u64 v[54:55], v[46:47], 0, s[14:15]
	v_lshl_add_u64 v[56:57], v[46:47], 0, s[16:17]
	v_lshl_add_u64 v[58:59], v[46:47], 0, s[34:35]
	s_waitcnt vmcnt(0)
	v_lshl_add_u64 v[60:61], v[46:47], 0, s[36:37]
	v_lshl_add_u64 v[62:63], v[46:47], 0, s[38:39]
	s_lshl_b32 s52, s25, 5
	s_mov_b32 s8, s25
	v_mov_b32_e32 v29, v28
	v_mov_b32_e32 v30, v28
	v_mov_b32_e32 v31, v28
	v_mov_b32_e32 v24, v28
	v_mov_b32_e32 v25, v28
	v_mov_b32_e32 v26, v28
	v_mov_b32_e32 v27, v28
	v_mov_b32_e32 v20, v28
	v_mov_b32_e32 v21, v28
	v_mov_b32_e32 v22, v28
	v_mov_b32_e32 v23, v28
	v_mov_b32_e32 v16, v28
	v_mov_b32_e32 v17, v28
	v_mov_b32_e32 v18, v28
	v_mov_b32_e32 v19, v28
	v_mov_b32_e32 v12, v28
	v_mov_b32_e32 v13, v28
	v_mov_b32_e32 v14, v28
	v_mov_b32_e32 v15, v28
	v_mov_b32_e32 v8, v28
	v_mov_b32_e32 v9, v28
	v_mov_b32_e32 v10, v28
	v_mov_b32_e32 v11, v28
	v_mov_b32_e32 v4, v28
	v_mov_b32_e32 v5, v28
	v_mov_b32_e32 v6, v28
	v_mov_b32_e32 v7, v28
	v_mov_b32_e32 v0, v28
	v_mov_b32_e32 v1, v28
	v_mov_b32_e32 v2, v28
	v_mov_b32_e32 v3, v28
.LBB0_881:
	s_ashr_i32 s53, s52, 31
	s_lshl_b64 s[46:47], s[52:53], 1
	v_lshl_add_u64 v[100:101], v[48:49], 0, s[46:47]
	v_lshl_add_u64 v[108:109], v[46:47], 0, s[46:47]
	v_lshl_add_u64 v[112:113], v[50:51], 0, s[46:47]
	v_lshl_add_u64 v[114:115], v[52:53], 0, s[46:47]
	v_lshl_add_u64 v[116:117], v[54:55], 0, s[46:47]
	v_lshl_add_u64 v[118:119], v[56:57], 0, s[46:47]
	v_lshl_add_u64 v[120:121], v[58:59], 0, s[46:47]
	v_lshl_add_u64 v[122:123], v[60:61], 0, s[46:47]
	v_lshl_add_u64 v[124:125], v[62:63], 0, s[46:47]
	global_load_dwordx4 v[126:129], v[100:101], off
	global_load_dwordx4 v[130:133], v[108:109], off
	global_load_dwordx4 v[142:145], v[112:113], off
	s_nop 0
	global_load_dwordx4 v[166:169], v[100:101], off offset:512
	s_nop 0
	s_nop 0
	global_load_dwordx4 v[194:197], v[108:109], off offset:512
	s_mov_b32 s33, s8
	s_add_i32 s8, s8, 16
	s_addk_i32 s52, 0x200
	s_cmp_lt_i32 s33, 8
	global_load_dwordx4 v[198:201], v[112:113], off offset:512
	s_waitcnt vmcnt(0)
	v_mfma_f32_16x16x32_bf16 v[28:31], v[126:129], v[130:133], v[28:31]
	v_mfma_f32_16x16x32_bf16 v[24:27], v[126:129], v[142:145], v[24:27]
	v_mfma_f32_16x16x32_bf16 v[28:31], v[166:169], v[194:197], v[28:31]
	v_mfma_f32_16x16x32_bf16 v[24:27], v[166:169], v[198:201], v[24:27]
	s_cbranch_scc1 .LBB0_881
; #define LAS __attribute__((address_space(3)))
; template <int NB>
; __device__ __forceinline__ void small_core(LAS unsigned char* lds, const bf16_t* A, int lda, const bf16_t* B0, const bf16_t* B1, int K, f32x4 (&out)[NB]) {
;     ...
;     if (st < nsteps) {
;         const int k = st * 32;
;         bf16x8 b[NB]; b[0] = *(const bf16x8*)(bp0 + k); if (NB == 2) b[NB - 1] = *(const bf16x8*)(bp1 + k);
;         bf16x8 a[8];
; #pragma unroll
;         for (int mb = 0; mb < 8; ++mb) a[mb] = *(const bf16x8*)(ap + (size_t)(16 * mb) * lda + k);
; #pragma unroll
;         for (int mb = 0; mb < 8; ++mb)
; #pragma unroll
;             for (int nb = 0; nb < NB; ++nb) acc[nb][mb] = __builtin_amdgcn_mfma_f32_16x16x32_bf16(b[nb], a[mb], acc[nb][mb], 0, 0, 0);
;     }
;     LAS float* red = (LAS float*)lds;
;     __syncthreads();
; #pragma unroll
;     for (int nb = 0; nb < NB; ++nb)
; #pragma unroll
;         for (int mb = 0; mb < 8; ++mb) *(LAS f32x4*)(red + ((w * 128 + 16 * mb + fr) * (16 * NB) + nb * 16 + 4 * fq)) = acc[nb][mb];
;     __syncthreads();
;     const int row = tid >> 2, c4 = (tid & 3) * 4;
; #pragma unroll
;     for (int nb = 0; nb < NB; ++nb) { f32x4 s = (f32x4){0.f, 0.f, 0.f, 0.f};
; #pragma unroll
;         for (int w8 = 0; w8 < 8; ++w8) s += *(const LAS f32x4*)(red + ((w8 * 128 + row) * (16 * NB) + nb * 16 + c4));
;         out[nb] = s; }
;     __syncthreads();
; }
; __device__ __forceinline__ void small_swiglu(LAS unsigned char* lds, const bf16_t* A, const bf16_t* Bt, bf16_t* ACT, const float* ssq, const float* biasw, int G, int c) {
;     for (int un = c; un < DFF / 16; un += G) {
;         const int j0 = 16 * un, rg = (j0 >> 7) * 256 + (j0 & 127);
;         f32x4 o[2]; small_core<2>(lds, A, 1024, Bt + (size_t)rg * 1024, Bt + (size_t)(rg + 128) * 1024, 1024, o);
;         const int row = threadIdx.x >> 2, c4 = (threadIdx.x & 3) * 4, b = 16 + (row >> 4);
;         const float rstd = __builtin_amdgcn_rsqf(ssq[NP + row] * (1.0f / 1024.0f) + EPS);
;         const f32x4 g = o[0] * rstd + *(const f32x4*)(biasw + (size_t)b * 5632 + rg + c4), uu = o[1] * rstd + *(const f32x4*)(biasw + (size_t)b * 5632 + rg + 128 + c4);
;         u32x2 wv; wv.x = pk2(silu_f(g[0]) * uu[0], silu_f(g[1]) * uu[1]); wv.y = pk2(silu_f(g[2]) * uu[2], silu_f(g[3]) * uu[3]);
;         *(u32x2*)(ACT + (size_t)(NP + row) * DFF + j0 + c4) = wv;
;     }
; }
.LBB0_882:
	s_cmp_gt_u32 s8, 31
	s_cbranch_scc1 .LBB0_884
	s_lshl_b32 s8, s8, 6
	v_lshl_add_u64 v[48:49], v[48:49], 0, s[8:9]
	global_load_dwordx4 v[126:129], v[48:49], off
	v_lshl_add_u64 v[46:47], v[46:47], 0, s[8:9]
	global_load_dwordx4 v[130:133], v[46:47], off
	v_add_co_u32_e32 v56, vcc, 0x8000, v46
	v_addc_co_u32_e32 v57, vcc, 0, v47, vcc
	v_add_co_u32_e32 v60, vcc, 0x10000, v46
	global_load_dwordx4 v[142:145], v[56:57], off
	s_nop 0
	v_addc_co_u32_e32 v61, vcc, 0, v47, vcc
	v_add_co_u32_e32 v68, vcc, 0x18000, v46
	v_addc_co_u32_e32 v69, vcc, 0, v47, vcc
	v_add_co_u32_e32 v72, vcc, 0x20000, v46
	s_nop 0
	v_addc_co_u32_e32 v73, vcc, 0, v47, vcc
	v_add_co_u32_e32 v76, vcc, 0x28000, v46
	s_nop 0
	v_addc_co_u32_e32 v77, vcc, 0, v47, vcc
	v_add_co_u32_e32 v56, vcc, 0x30000, v46
	v_addc_co_u32_e32 v57, vcc, 0, v47, vcc
	v_add_co_u32_e32 v46, vcc, 0x38000, v46
	s_nop 0
	v_addc_co_u32_e32 v47, vcc, 0, v47, vcc
	s_waitcnt vmcnt(0)
	v_mfma_f32_16x16x32_bf16 v[28:31], v[126:129], v[130:133], v[28:31]
	v_mfma_f32_16x16x32_bf16 v[24:27], v[126:129], v[142:145], v[24:27]
.LBB0_884:
	s_lshl_b32 s8, s25, 13
	v_lshlrev_b32_e32 v32, 6, v66
	s_add_i32 s8, s8, 0
	v_add3_u32 v32, s8, v44, v32
	s_barrier
	ds_write_b128 v32, v[28:31]
	ds_write_b128 v32, v[24:27] offset:1024
	ds_write_b128 v32, v[20:23] offset:2048
	ds_write_b128 v32, v[16:19] offset:3072
	ds_write_b128 v32, v[12:15] offset:4096
	ds_write_b128 v32, v[8:11] offset:5120
	ds_write_b128 v32, v[4:7] offset:6144
	ds_write_b128 v32, v[0:3] offset:7168
	v_lshlrev_b32_e32 v0, 4, v65
	v_or_b32_e32 v44, s40, v64
	v_and_b32_e32 v1, 48, v0
	v_and_b32_e32 v0, 0xffffffc0, v0
	v_ashrrev_i32_e32 v45, 31, v44
	v_add3_u32 v28, 0, v1, v0
	v_lshl_add_u64 v[56:57], v[44:45], 1, v[34:35]
	v_lshlrev_b64 v[52:53], 2, v[44:45]
	s_waitcnt lgkmcnt(0)
	s_barrier
	ds_read_b128 v[0:3], v28
	ds_read_b128 v[4:7], v28 offset:8192
	ds_read_b128 v[8:11], v28 offset:16384
	ds_read_b128 v[12:15], v28 offset:24576
	ds_read_b128 v[16:19], v28 offset:32768
	ds_read_b128 v[20:23], v28 offset:40960
	ds_read_b128 v[24:27], v28 offset:49152
	ds_read_b128 v[28:31], v28 offset:57344
	s_waitcnt lgkmcnt(0)
	s_barrier
	v_readfirstlane_b32 s100, v178
	s_cmpk_gt_u32 s100, 0x7f
	s_cbranch_scc1 .LBB0_878
	global_load_dwordx2 v[58:59], v[56:57], off
	v_lshl_add_u64 v[44:45], v[36:37], 0, v[52:53]
	global_load_dwordx4 v[44:47], v[44:45], off
	v_lshl_add_u64 v[48:49], v[38:39], 0, v[52:53]
	global_load_dwordx4 v[48:51], v[48:49], off
	v_lshl_add_u64 v[52:53], v[40:41], 0, v[52:53]
	global_load_dwordx4 v[52:55], v[52:53], off
	v_pk_add_f32 v[0:1], v[0:1], 0 op_sel_hi:[1,0]
	v_pk_add_f32 v[2:3], v[2:3], 0 op_sel_hi:[1,0]
	v_pk_add_f32 v[0:1], v[0:1], v[4:5]
	v_pk_add_f32 v[2:3], v[2:3], v[6:7]
	v_pk_add_f32 v[0:1], v[0:1], v[8:9]
	v_pk_add_f32 v[2:3], v[2:3], v[10:11]
	v_pk_add_f32 v[0:1], v[0:1], v[12:13]
	v_pk_add_f32 v[2:3], v[2:3], v[14:15]
	v_pk_add_f32 v[0:1], v[0:1], v[16:17]
	v_pk_add_f32 v[2:3], v[2:3], v[18:19]
	v_pk_add_f32 v[0:1], v[0:1], v[20:21]
	v_pk_add_f32 v[2:3], v[2:3], v[22:23]
	v_pk_add_f32 v[0:1], v[0:1], v[24:25]
	v_pk_add_f32 v[2:3], v[2:3], v[26:27]
	v_pk_add_f32 v[0:1], v[0:1], v[28:29]
	v_pk_add_f32 v[2:3], v[2:3], v[30:31]
	s_waitcnt vmcnt(3)
	v_lshlrev_b32_e32 v4, 16, v58
	v_and_b32_e32 v5, 0xffff0000, v58
	s_waitcnt vmcnt(2)
	v_pk_mul_f32 v[4:5], v[44:45], v[4:5]
	v_lshlrev_b32_e32 v6, 16, v59
	v_and_b32_e32 v7, 0xffff0000, v59
	s_waitcnt vmcnt(1)
	v_pk_fma_f32 v[4:5], v[0:1], v[48:49], v[4:5]
	v_pk_mul_f32 v[6:7], v[46:47], v[6:7]
	v_mul_f32_e32 v0, v5, v5
	v_pk_fma_f32 v[2:3], v[2:3], v[50:51], v[6:7]
	v_fmac_f32_e32 v0, v4, v4
	v_fmac_f32_e32 v0, v2, v2
	v_fmac_f32_e32 v0, v3, v3
	ds_bpermute_b32 v1, v181, v0
	s_waitcnt vmcnt(0)
	v_pk_mul_f32 v[2:3], v[54:55], v[2:3]
	v_pk_mul_f32 v[4:5], v[52:53], v[4:5]
	s_waitcnt lgkmcnt(0)
	v_add_f32_e32 v0, v0, v1
	ds_bpermute_b32 v1, v245, v0
	v_cvt_pk_bf16_f32 v4, v4, v5
	v_cvt_pk_bf16_f32 v5, v2, v3
	global_store_dwordx2 v[56:57], v[4:5], off
	s_and_saveexec_b64 s[40:41], s[0:1]
	s_cbranch_execz .LBB0_878
	s_waitcnt lgkmcnt(0)
	v_add_f32_e32 v0, v0, v1
	global_atomic_add_f32 v[42:43], v0, off
	s_branch .LBB0_878

; #define LAS __attribute__((address_space(3)))
; __device__ __forceinline__ void small_resid(LAS unsigned char* lds, const bf16_t* A, int K, const bf16_t* Bt, const float* xs_in, float* X, const float* modp, float coef, ...
;     for (int un = c; un < 64; un += G) {
;         f32x4 o[1]; small_core<1>(lds, A, K, Bt + (size_t)(16 * un) * K, Bt, K, o);
;         const int row = threadIdx.x >> 2, col = 16 * un + (threadIdx.x & 3) * 4, b = 16 + (row >> 4);
;         f32x4 bs;
;         if (xs_in) bs = *(const f32x4*)(xs_in + (size_t)row * DM + col);
;         else { const u32x2 r_ = *(const u32x2*)(An + (size_t)(NP + row) * DM + col); const f32x4 rg = *(const f32x4*)(rgs + (size_t)b * 1024 + col);
; __global__ void __launch_bounds__(512, 2) fwd_kernel(Params P) {
;     ...
;         small_resid(lds, OC + (size_t)NP * DM, 1024, WCO, nullptr, X, MOD + (size_t)24 * 9216 + (size_t)5 * 1024, 1.0f, SSQ + 5 * 33024, GS + 5 * 24 * 1024, RGS + 4 * 24 * 1024, H, true, G, c);
.LBB0_1601:
	s_or_b64 exec, exec, s[0:1]
	s_add_u32 s22, s92, 0xdd000
	s_addc_u32 s23, s93, 0
	s_add_u32 s28, s92, 0x1e308000
	s_addc_u32 s29, s93, 0
	s_add_u32 s30, s92, 0x1e887c00
	s_addc_u32 s31, s93, 0
	s_and_b64 vcc, exec, s[6:7]
	v_and_b32_e32 v228, 12, v239
	s_waitcnt lgkmcnt(0)
	s_barrier
	s_and_b32 s99, s2, 3
	s_mov_b32 s101, 0
	v_lshlrev_b32_e32 v0, 9, v178
	v_and_b32_e32 v32, 0x7f800, v0
	v_mov_b32_e32 v33, 0
	v_or_b32_e32 v2, 16, v179
	v_lshl_add_u32 v2, s99, 1, v2
	v_lshl_add_u64 v[0:1], s[42:43], 0, v[32:33]
	s_mov_b64 s[0:1], 0x4000000
	s_waitcnt vmcnt(1)
	v_lshl_add_u64 v[34:35], v[0:1], 0, s[0:1]
	s_mul_i32 s100, s99, 0x10000
	v_lshl_add_u64 v[34:35], v[34:35], 0, s[100:101]
	v_lshlrev_b32_e32 v32, 12, v2
	s_mov_b32 s0, 0x9000
	v_mov_b64_e32 v[0:1], s[22:23]
	v_lshl_add_u64 v[36:37], s[30:31], 0, v[32:33]
	s_waitcnt vmcnt(0)
	v_mad_u64_u32 v[38:39], s[0:1], v2, s0, v[0:1]
	v_lshl_add_u64 v[40:41], s[28:29], 0, v[32:33]
	v_and_b32_e32 v0, 3, v178
	v_and_b32_e32 v32, 0x3fc, v178
	s_add_u32 s4, s92, 0x19540000
	v_cmp_eq_u32_e64 s[0:1], 0, v0
	v_lshl_add_u64 v[0:1], s[92:93], 0, v[32:33]
	s_mov_b64 s[14:15], 0x1e807400
	s_addc_u32 s5, s93, 0
	s_mov_b32 s13, 0
	v_lshl_add_u64 v[42:43], v[0:1], 0, s[14:15]
	s_mul_i32 s100, s99, 0x80
	v_lshl_add_u64 v[42:43], v[42:43], 0, s[100:101]
	s_mov_b64 s[14:15], 0x8000
	s_mov_b64 s[16:17], 0x10000
	s_mov_b64 s[18:19], 0x18000
	s_mov_b64 s[20:21], 0x20000
	s_mov_b64 s[34:35], 0x28000
	s_mov_b64 s[36:37], 0x30000
	s_mov_b64 s[38:39], 0x38000
	s_mul_hi_u32 s3, s2, 0x40000000
	s_branch .LBB0_1604

; #define LAS __attribute__((address_space(3)))
; template <int NB>
; __device__ __forceinline__ void small_core(LAS unsigned char* lds, const bf16_t* A, int lda, const bf16_t* B0, const bf16_t* B1, int K, f32x4 (&out)[NB]) {
;     int tid_ = threadIdx.x; asm volatile("" : "+v"(tid_));
;     const int tid = tid_, lane = tid & 63, w = __builtin_amdgcn_readfirstlane(tid >> 6), fr = lane & 15, fq = lane >> 4;
;     f32x4 acc[NB][8];
; #pragma unroll
;     for (int nb = 0; nb < NB; ++nb)
; #pragma unroll
;         for (int mb = 0; mb < 8; ++mb) acc[nb][mb] = (f32x4){0.f, 0.f, 0.f, 0.f};
;     const bf16_t* ap = A + (size_t)fr * lda + 8 * fq;
;     const bf16_t* bp0 = B0 + (size_t)fr * K + 8 * fq;
;     const bf16_t* bp1 = B1 + (size_t)fr * K + 8 * fq;
;     const int nsteps = K >> 5;
;     int st = w;
;     for (; st + 8 < nsteps; st += 16) {
;         const int k = st * 32, k2 = k + 256;
;         bf16x8 b[NB], b2[NB]; b[0] = *(const bf16x8*)(bp0 + k); b2[0] = *(const bf16x8*)(bp0 + k2);
;         if (NB == 2) { b[NB - 1] = *(const bf16x8*)(bp1 + k); b2[NB - 1] = *(const bf16x8*)(bp1 + k2); }
;         bf16x8 a[8], a2[8];
; #pragma unroll
;         for (int mb = 0; mb < 8; ++mb) { a[mb] = *(const bf16x8*)(ap + (size_t)(16 * mb) * lda + k); a2[mb] = *(const bf16x8*)(ap + (size_t)(16 * mb) * lda + k2); }
; #pragma unroll
;         for (int mb = 0; mb < 8; ++mb)
; #pragma unroll
;             for (int nb = 0; nb < NB; ++nb) { acc[nb][mb] = __builtin_amdgcn_mfma_f32_16x16x32_bf16(b[nb], a[mb], acc[nb][mb], 0, 0, 0);
;                 acc[nb][mb] = __builtin_amdgcn_mfma_f32_16x16x32_bf16(b2[nb], a2[mb], acc[nb][mb], 0, 0, 0); }
;     }
.LBB0_1604:
	s_lshl_b32 s40, s3, 4
	s_ashr_i32 s41, s40, 31
	v_mov_b32_e32 v64, v178
	s_lshl_b64 s[46:47], s[40:41], 11
	s_add_u32 s46, s26, s46
	v_and_b32_e32 v65, 15, v64
	v_bfe_u32 v2, v64, 4, 2
	v_lshlrev_b32_e32 v32, 11, v65
	s_addc_u32 s47, s27, s47
	v_readfirstlane_b32 s12, v64
	s_waitcnt lgkmcnt(0)
	v_lshl_add_u64 v[0:1], s[4:5], 0, v[32:33]
	v_lshlrev_b32_e32 v44, 4, v2
	v_mov_b32_e32 v45, v33
	s_ashr_i32 s25, s12, 6
	v_lshl_add_u64 v[46:47], v[0:1], 0, v[44:45]
	s_mul_i32 s100, s99, 0x10000
	v_lshl_add_u64 v[46:47], v[46:47], 0, s[100:101]
	v_lshl_add_u64 v[0:1], s[46:47], 0, v[32:33]
	v_lshl_add_u64 v[48:49], v[0:1], 0, v[44:45]
	s_cmp_gt_i32 s25, 23
	v_mov_b32_e32 v3, 0
	v_mov_b32_e32 v2, 0
	v_mov_b32_e32 v1, 0
	v_mov_b32_e32 v0, 0
	v_mov_b32_e32 v7, 0
	v_mov_b32_e32 v6, 0
	v_mov_b32_e32 v5, 0
	v_mov_b32_e32 v4, 0
	v_mov_b32_e32 v11, 0
	v_mov_b32_e32 v10, 0
	v_mov_b32_e32 v9, 0
	v_mov_b32_e32 v8, 0
	v_mov_b32_e32 v15, 0
	v_mov_b32_e32 v14, 0
	v_mov_b32_e32 v13, 0
	v_mov_b32_e32 v12, 0
	v_mov_b32_e32 v19, 0
	v_mov_b32_e32 v18, 0
	v_mov_b32_e32 v17, 0
	v_mov_b32_e32 v16, 0
	v_mov_b32_e32 v23, 0
	v_mov_b32_e32 v22, 0
	v_mov_b32_e32 v21, 0
	v_mov_b32_e32 v20, 0
	v_mov_b32_e32 v27, 0
	v_mov_b32_e32 v26, 0
	v_mov_b32_e32 v25, 0
	v_mov_b32_e32 v24, 0
	v_mov_b32_e32 v31, 0
	v_mov_b32_e32 v30, 0
	v_mov_b32_e32 v29, 0
	v_mov_b32_e32 v28, 0
	s_mov_b32 s12, s25
	s_cbranch_scc1 .LBB0_1607
	v_mov_b32_e32 v28, 0
	v_lshl_add_u64 v[50:51], v[46:47], 0, s[14:15]
	v_lshl_add_u64 v[52:53], v[46:47], 0, s[16:17]
	v_lshl_add_u64 v[54:55], v[46:47], 0, s[18:19]
	v_lshl_add_u64 v[56:57], v[46:47], 0, s[20:21]
	v_lshl_add_u64 v[58:59], v[46:47], 0, s[34:35]
	v_lshl_add_u64 v[60:61], v[46:47], 0, s[36:37]
	v_lshl_add_u64 v[62:63], v[46:47], 0, s[38:39]
	s_lshl_b32 s52, s25, 5
	s_mov_b32 s12, s25
	v_mov_b32_e32 v29, v28
	v_mov_b32_e32 v30, v28
	v_mov_b32_e32 v31, v28
	v_mov_b32_e32 v24, v28
	v_mov_b32_e32 v25, v28
	v_mov_b32_e32 v26, v28
	v_mov_b32_e32 v27, v28
	v_mov_b32_e32 v20, v28
	v_mov_b32_e32 v21, v28
	v_mov_b32_e32 v22, v28
	v_mov_b32_e32 v23, v28
	v_mov_b32_e32 v16, v28
	v_mov_b32_e32 v17, v28
	v_mov_b32_e32 v18, v28
	v_mov_b32_e32 v19, v28
	v_mov_b32_e32 v12, v28
	v_mov_b32_e32 v13, v28
	v_mov_b32_e32 v14, v28
	v_mov_b32_e32 v15, v28
	v_mov_b32_e32 v8, v28
	v_mov_b32_e32 v9, v28
	v_mov_b32_e32 v10, v28
	v_mov_b32_e32 v11, v28
	v_mov_b32_e32 v4, v28
	v_mov_b32_e32 v5, v28
	v_mov_b32_e32 v6, v28
	v_mov_b32_e32 v7, v28
	v_mov_b32_e32 v0, v28
	v_mov_b32_e32 v1, v28
	v_mov_b32_e32 v2, v28
	v_mov_b32_e32 v3, v28
.LBB0_1606:
	s_ashr_i32 s53, s52, 31
	s_lshl_b64 s[46:47], s[52:53], 1
	v_lshl_add_u64 v[98:99], v[48:49], 0, s[46:47]
	v_lshl_add_u64 v[106:107], v[46:47], 0, s[46:47]
	v_lshl_add_u64 v[110:111], v[50:51], 0, s[46:47]
	v_lshl_add_u64 v[112:113], v[52:53], 0, s[46:47]
	v_lshl_add_u64 v[114:115], v[54:55], 0, s[46:47]
	v_lshl_add_u64 v[116:117], v[56:57], 0, s[46:47]
	v_lshl_add_u64 v[118:119], v[58:59], 0, s[46:47]
	v_lshl_add_u64 v[120:121], v[60:61], 0, s[46:47]
	v_lshl_add_u64 v[122:123], v[62:63], 0, s[46:47]
	global_load_dwordx4 v[124:127], v[98:99], off
	global_load_dwordx4 v[128:131], v[106:107], off
	global_load_dwordx4 v[132:135], v[110:111], off
	s_nop 0
	global_load_dwordx4 v[156:159], v[98:99], off offset:512
	s_nop 0
	s_nop 0
	global_load_dwordx4 v[164:167], v[106:107], off offset:512
	s_mov_b32 s33, s12
	s_add_i32 s12, s12, 16
	s_addk_i32 s52, 0x200
	s_cmp_lt_i32 s33, 8
	global_load_dwordx4 v[168:171], v[110:111], off offset:512
	s_waitcnt vmcnt(0)
	v_mfma_f32_16x16x32_bf16 v[28:31], v[124:127], v[128:131], v[28:31]
	v_mfma_f32_16x16x32_bf16 v[24:27], v[124:127], v[132:135], v[24:27]
	v_mfma_f32_16x16x32_bf16 v[28:31], v[156:159], v[164:167], v[28:31]
	v_mfma_f32_16x16x32_bf16 v[24:27], v[156:159], v[168:171], v[24:27]
	s_cbranch_scc1 .LBB0_1606
; #define LAS __attribute__((address_space(3)))
; template <int NB>
; __device__ __forceinline__ void small_core(LAS unsigned char* lds, const bf16_t* A, int lda, const bf16_t* B0, const bf16_t* B1, int K, f32x4 (&out)[NB]) {
;     ...
;     if (st < nsteps) {
;         const int k = st * 32;
;         bf16x8 b[NB]; b[0] = *(const bf16x8*)(bp0 + k); if (NB == 2) b[NB - 1] = *(const bf16x8*)(bp1 + k);
;         bf16x8 a[8];
; #pragma unroll
;         for (int mb = 0; mb < 8; ++mb) a[mb] = *(const bf16x8*)(ap + (size_t)(16 * mb) * lda + k);
; #pragma unroll
;         for (int mb = 0; mb < 8; ++mb)
; #pragma unroll
;             for (int nb = 0; nb < NB; ++nb) acc[nb][mb] = __builtin_amdgcn_mfma_f32_16x16x32_bf16(b[nb], a[mb], acc[nb][mb], 0, 0, 0);
;     }
;     LAS float* red = (LAS float*)lds;
;     __syncthreads();
; #pragma unroll
;     for (int nb = 0; nb < NB; ++nb)
; #pragma unroll
;         for (int mb = 0; mb < 8; ++mb) *(LAS f32x4*)(red + ((w * 128 + 16 * mb + fr) * (16 * NB) + nb * 16 + 4 * fq)) = acc[nb][mb];
;     __syncthreads();
;     const int row = tid >> 2, c4 = (tid & 3) * 4;
; #pragma unroll
;     for (int nb = 0; nb < NB; ++nb) { f32x4 s = (f32x4){0.f, 0.f, 0.f, 0.f};
; #pragma unroll
;         for (int w8 = 0; w8 < 8; ++w8) s += *(const LAS f32x4*)(red + ((w8 * 128 + row) * (16 * NB) + nb * 16 + c4));
;         out[nb] = s; }
;     __syncthreads();
; }
; __device__ __forceinline__ void small_swiglu(LAS unsigned char* lds, const bf16_t* A, const bf16_t* Bt, bf16_t* ACT, const float* ssq, const float* biasw, int G, int c) {
;     for (int un = c; un < DFF / 16; un += G) {
;         const int j0 = 16 * un, rg = (j0 >> 7) * 256 + (j0 & 127);
;         f32x4 o[2]; small_core<2>(lds, A, 1024, Bt + (size_t)rg * 1024, Bt + (size_t)(rg + 128) * 1024, 1024, o);
;         const int row = threadIdx.x >> 2, c4 = (threadIdx.x & 3) * 4, b = 16 + (row >> 4);
;         const float rstd = __builtin_amdgcn_rsqf(ssq[NP + row] * (1.0f / 1024.0f) + EPS);
;         const f32x4 g = o[0] * rstd + *(const f32x4*)(biasw + (size_t)b * 5632 + rg + c4), uu = o[1] * rstd + *(const f32x4*)(biasw + (size_t)b * 5632 + rg + 128 + c4);
;         u32x2 wv; wv.x = pk2(silu_f(g[0]) * uu[0], silu_f(g[1]) * uu[1]); wv.y = pk2(silu_f(g[2]) * uu[2], silu_f(g[3]) * uu[3]);
;         *(u32x2*)(ACT + (size_t)(NP + row) * DFF + j0 + c4) = wv;
;     }
; }
.LBB0_1607:
	s_cmp_gt_u32 s12, 31
	s_cbranch_scc1 .LBB0_1609
	s_lshl_b32 s12, s12, 6
	v_lshl_add_u64 v[48:49], v[48:49], 0, s[12:13]
	global_load_dwordx4 v[124:127], v[48:49], off
	v_lshl_add_u64 v[46:47], v[46:47], 0, s[12:13]
	global_load_dwordx4 v[128:131], v[46:47], off
	v_add_co_u32_e32 v56, vcc, 0x8000, v46
	v_addc_co_u32_e32 v57, vcc, 0, v47, vcc
	v_add_co_u32_e32 v60, vcc, 0x10000, v46
	s_nop 1
	v_addc_co_u32_e32 v61, vcc, 0, v47, vcc
	v_add_co_u32_e32 v66, vcc, 0x18000, v46
	global_load_dwordx4 v[132:135], v[56:57], off
	s_nop 0
	v_addc_co_u32_e32 v67, vcc, 0, v47, vcc
	v_add_co_u32_e32 v70, vcc, 0x20000, v46
	v_addc_co_u32_e32 v71, vcc, 0, v47, vcc
	v_add_co_u32_e32 v70, vcc, 0x28000, v46
	s_nop 0
	v_addc_co_u32_e32 v71, vcc, 0, v47, vcc
	v_add_co_u32_e32 v60, vcc, 0x30000, v46
	s_nop 0
	v_addc_co_u32_e32 v61, vcc, 0, v47, vcc
	v_add_co_u32_e32 v46, vcc, 0x38000, v46
	s_nop 0
	v_addc_co_u32_e32 v47, vcc, 0, v47, vcc
	s_waitcnt vmcnt(0)
	v_mfma_f32_16x16x32_bf16 v[28:31], v[124:127], v[128:131], v[28:31]
	v_mfma_f32_16x16x32_bf16 v[24:27], v[124:127], v[132:135], v[24:27]
.LBB0_1609:
	s_lshl_b32 s12, s25, 13
	v_lshlrev_b32_e32 v32, 6, v65
	s_add_i32 s12, s12, 0
	v_add3_u32 v32, s12, v44, v32
	s_barrier
	ds_write_b128 v32, v[28:31]
	ds_write_b128 v32, v[24:27] offset:1024
	ds_write_b128 v32, v[20:23] offset:2048
	ds_write_b128 v32, v[16:19] offset:3072
	ds_write_b128 v32, v[12:15] offset:4096
	ds_write_b128 v32, v[8:11] offset:5120
	ds_write_b128 v32, v[4:7] offset:6144
	ds_write_b128 v32, v[0:3] offset:7168
	v_lshlrev_b32_e32 v0, 4, v64
	v_or_b32_e32 v44, s40, v228
	v_and_b32_e32 v1, 48, v0
	v_and_b32_e32 v0, 0xffffffc0, v0
	v_ashrrev_i32_e32 v45, 31, v44
	v_add3_u32 v28, 0, v1, v0
	v_lshl_add_u64 v[56:57], v[44:45], 1, v[34:35]
	v_lshlrev_b64 v[52:53], 2, v[44:45]
	s_waitcnt lgkmcnt(0)
	s_barrier
	ds_read_b128 v[0:3], v28
	ds_read_b128 v[4:7], v28 offset:8192
	ds_read_b128 v[8:11], v28 offset:16384
	ds_read_b128 v[12:15], v28 offset:24576
	ds_read_b128 v[16:19], v28 offset:32768
	ds_read_b128 v[20:23], v28 offset:40960
	ds_read_b128 v[24:27], v28 offset:49152
	ds_read_b128 v[28:31], v28 offset:57344
	s_waitcnt lgkmcnt(0)
	s_barrier
	v_readfirstlane_b32 s100, v178
	s_cmpk_gt_u32 s100, 0x7f
	s_cbranch_scc1 .LBB0_1603
	global_load_dwordx2 v[58:59], v[56:57], off
	v_lshl_add_u64 v[44:45], v[36:37], 0, v[52:53]
	global_load_dwordx4 v[44:47], v[44:45], off
	v_lshl_add_u64 v[48:49], v[38:39], 0, v[52:53]
	global_load_dwordx4 v[48:51], v[48:49], off
	v_lshl_add_u64 v[52:53], v[40:41], 0, v[52:53]
	global_load_dwordx4 v[52:55], v[52:53], off
	v_pk_add_f32 v[0:1], v[0:1], 0 op_sel_hi:[1,0]
	v_pk_add_f32 v[2:3], v[2:3], 0 op_sel_hi:[1,0]
	v_pk_add_f32 v[0:1], v[0:1], v[4:5]
	v_pk_add_f32 v[2:3], v[2:3], v[6:7]
	v_pk_add_f32 v[0:1], v[0:1], v[8:9]
	v_pk_add_f32 v[2:3], v[2:3], v[10:11]
	v_pk_add_f32 v[0:1], v[0:1], v[12:13]
	v_pk_add_f32 v[2:3], v[2:3], v[14:15]
	v_pk_add_f32 v[0:1], v[0:1], v[16:17]
	v_pk_add_f32 v[2:3], v[2:3], v[18:19]
	v_pk_add_f32 v[0:1], v[0:1], v[20:21]
	v_pk_add_f32 v[2:3], v[2:3], v[22:23]
	v_pk_add_f32 v[0:1], v[0:1], v[24:25]
	v_pk_add_f32 v[2:3], v[2:3], v[26:27]
	v_pk_add_f32 v[0:1], v[0:1], v[28:29]
	v_pk_add_f32 v[2:3], v[2:3], v[30:31]
	s_waitcnt vmcnt(3)
	v_lshlrev_b32_e32 v4, 16, v58
	v_and_b32_e32 v5, 0xffff0000, v58
	s_waitcnt vmcnt(2)
	v_pk_mul_f32 v[4:5], v[44:45], v[4:5]
	v_lshlrev_b32_e32 v6, 16, v59
	v_and_b32_e32 v7, 0xffff0000, v59
	s_waitcnt vmcnt(1)
	v_pk_fma_f32 v[4:5], v[0:1], v[48:49], v[4:5]
	v_pk_mul_f32 v[6:7], v[46:47], v[6:7]
	v_mul_f32_e32 v0, v5, v5
	v_pk_fma_f32 v[2:3], v[2:3], v[50:51], v[6:7]
	v_fmac_f32_e32 v0, v4, v4
	v_fmac_f32_e32 v0, v2, v2
	v_fmac_f32_e32 v0, v3, v3
	ds_bpermute_b32 v1, v181, v0
	s_waitcnt vmcnt(0)
	v_pk_mul_f32 v[2:3], v[54:55], v[2:3]
	v_pk_mul_f32 v[4:5], v[52:53], v[4:5]
	s_waitcnt lgkmcnt(0)
	v_add_f32_e32 v0, v0, v1
	ds_bpermute_b32 v1, v245, v0
	v_cvt_pk_bf16_f32 v4, v4, v5
	v_cvt_pk_bf16_f32 v5, v2, v3
	global_store_dwordx2 v[56:57], v[4:5], off
	s_and_saveexec_b64 s[40:41], s[0:1]
	s_cbranch_execz .LBB0_1603
	s_waitcnt lgkmcnt(0)
	v_add_f32_e32 v0, v0, v1
	global_atomic_add_f32 v[42:43], v0, off
	s_branch .LBB0_1603

; __global__ void __launch_bounds__(512, 2) fwd_kernel(Params P) {
;     ...
;         { const long total = (long)8 * 496 * 256;
;           for (long i = gtid; i < total; i += gthreads) { const int cc = (int)(i & 255); const long br = i >> 8; const int j = (int)(br % 496), b = (int)(br / 496);
;               const size_t so = ((size_t)b * 512 + j + 16) * 1024 + cc * 4, dof = ((size_t)b * 512 + j) * 1024 + cc * 4;
;               *(f32x4*)(OUT + O_CKS + dof) = *(const f32x4*)(P.in[6] + so); *(f32x4*)(OUT + O_CVS + dof) = *(const f32x4*)(P.in[7] + so); } }
.LBB0_1894:
	v_ashrrev_i64 v[4:5], 8, v[176:177]
	v_ashrrev_i32_e32 v2, 31, v177
	v_mul_lo_u32 v6, v2, s12
	v_mad_u64_u32 v[10:11], s[16:17], v2, s13, 0
	v_mul_hi_u32 v2, v4, s13
	v_add3_u32 v11, v11, v6, v10
	v_mad_u64_u32 v[12:13], s[16:17], v5, s13, v[2:3]
	v_mad_u64_u32 v[10:11], s[16:17], v4, -1, v[10:11]
	v_mov_b32_e32 v2, v13
	v_mov_b32_e32 v13, v3
	v_sub_u32_e32 v6, v11, v5
	v_mad_u64_u32 v[12:13], s[16:17], v4, s12, v[12:13]
	v_mov_b32_e32 v7, v3
	v_sub_u32_e32 v11, v6, v4
	v_mov_b32_e32 v6, v13
	v_lshl_add_u64 v[6:7], v[2:3], 0, v[6:7]
	v_mad_u64_u32 v[6:7], s[16:17], v5, s12, v[6:7]
	v_lshl_add_u64 v[6:7], v[6:7], 0, v[10:11]
	v_mad_u64_u32 v[6:7], s[16:17], v4, 1, v[6:7]
	v_add_u32_e32 v7, v5, v7
	v_ashrrev_i64 v[10:11], 8, v[6:7]
	v_lshrrev_b32_e32 v2, 31, v7
	v_lshl_add_u64 v[6:7], v[10:11], 0, v[2:3]
	v_mad_u64_u32 v[10:11], s[16:17], v6, s14, 0
	v_mov_b32_e32 v2, v11
	v_mov_b32_e32 v8, v3
	v_mov_b32_e32 v9, v6
	v_mad_u64_u32 v[6:7], s[16:17], v7, s14, v[2:3]
	v_sub_co_u32_e32 v4, vcc, v4, v10
	v_ashrrev_i64 v[8:9], 23, v[8:9]
	s_nop 0
	v_subb_co_u32_e32 v5, vcc, v5, v6, vcc
	v_lshl_add_u64 v[4:5], v[8:9], 0, v[4:5]
	v_and_b32_e32 v14, 0x3fc, v0
	v_lshlrev_b64 v[8:9], 12, v[4:5]
	v_lshl_or_b32 v8, v14, 2, v8
	v_lshl_add_u64 v[10:11], v[8:9], 0, s[8:9]
	v_lshl_add_u64 v[4:5], s[20:21], 0, v[10:11]
	global_load_dwordx4 v[4:7], v[4:5], off
	v_lshl_add_u64 v[12:13], s[0:1], 0, v[8:9]
	v_lshl_add_u64 v[10:11], s[22:23], 0, v[10:11]
	global_load_dwordx4 v[248:251], v[10:11], off
	v_lshl_add_u64 v[176:177], v[176:177], 0, s[66:67]
	v_cmp_lt_i64_e32 vcc, s[10:11], v[176:177]
	v_lshl_add_u64 v[0:1], v[0:1], 0, s[4:5]
	s_or_b64 s[6:7], vcc, s[6:7]
	v_lshl_add_u64 v[8:9], s[2:3], 0, v[8:9]
	s_waitcnt vmcnt(0)
	global_store_dwordx4 v[12:13], v[4:7], off
	global_store_dwordx4 v[8:9], v[248:251], off
	s_andn2_b64 exec, exec, s[6:7]
	s_cbranch_execnz .LBB0_1894
